# phase 0: RoPE table on the last workgroup; modulation item issues all its loads up front
# baseline (speedup 1.0000x reference)
.LBB0_29:
	s_mul_hi_i32 s13, s10, 0x2aaaaaab
	s_lshr_b32 s14, s13, 31
	s_ashr_i32 s15, s13, 2
	s_add_i32 s15, s15, s14
	s_ashr_i32 s0, s15, 31
	s_lshr_b32 s0, s0, 28
	s_add_i32 s0, s15, s0
	s_and_b32 s0, s0, -16
	s_sub_i32 s11, s15, s0
	s_lshl_b32 s12, s11, 6
	s_ashr_i32 s0, s13, 6
	s_mul_i32 s15, s15, 24
	s_add_i32 s0, s0, s14
	s_sub_i32 s1, s10, s15
	v_lshl_add_u32 v2, s1, 8, v0
	s_ashr_i32 s1, s0, 31
	s_lshl_b64 s[2:3], s[0:1], 10
	s_ashr_i32 s1, s12, 31
	s_add_u32 s2, s2, s12
	s_addc_u32 s1, s3, s1
	s_mulk_i32 s1, 0x6000
	s_mul_hi_u32 s3, s2, 0x6000
	s_add_i32 s3, s3, s1
	s_mulk_i32 s2, 0x6000
	v_readlane_b32 s38, v247, 19
	v_readlane_b32 s39, v247, 20
	s_nop 1
	s_add_u32 s2, s38, s2
	s_addc_u32 s3, s39, s3
	s_mov_b32 s1, 0
	v_lshlrev_b32_e32 v14, 2, v2
	global_load_dword v96, v14, s[2:3]
	s_add_u32 s2, s2, 0x6000
	s_addc_u32 s3, s3, 0
	global_load_dword v97, v14, s[2:3]
	s_add_u32 s2, s2, 0x6000
	s_addc_u32 s3, s3, 0
	global_load_dword v98, v14, s[2:3]
	s_add_u32 s2, s2, 0x6000
	s_addc_u32 s3, s3, 0
	global_load_dword v99, v14, s[2:3]
	s_add_u32 s2, s2, 0x6000
	s_addc_u32 s3, s3, 0
	global_load_dword v100, v14, s[2:3]
	s_add_u32 s2, s2, 0x6000
	s_addc_u32 s3, s3, 0
	global_load_dword v101, v14, s[2:3]
	s_add_u32 s2, s2, 0x6000
	s_addc_u32 s3, s3, 0
	global_load_dword v102, v14, s[2:3]
	s_add_u32 s2, s2, 0x6000
	s_addc_u32 s3, s3, 0
	global_load_dword v103, v14, s[2:3]
	s_add_u32 s2, s2, 0x6000
	s_addc_u32 s3, s3, 0
	global_load_dword v104, v14, s[2:3]
	s_add_u32 s2, s2, 0x6000
	s_addc_u32 s3, s3, 0
	global_load_dword v105, v14, s[2:3]
	s_add_u32 s2, s2, 0x6000
	s_addc_u32 s3, s3, 0
	global_load_dword v106, v14, s[2:3]
	s_add_u32 s2, s2, 0x6000
	s_addc_u32 s3, s3, 0
	global_load_dword v107, v14, s[2:3]
	s_add_u32 s2, s2, 0x6000
	s_addc_u32 s3, s3, 0
	global_load_dword v108, v14, s[2:3]
	s_add_u32 s2, s2, 0x6000
	s_addc_u32 s3, s3, 0
	global_load_dword v109, v14, s[2:3]
	s_add_u32 s2, s2, 0x6000
	s_addc_u32 s3, s3, 0
	global_load_dword v110, v14, s[2:3]
	s_add_u32 s2, s2, 0x6000
	s_addc_u32 s3, s3, 0
	global_load_dword v111, v14, s[2:3]
	s_add_u32 s2, s2, 0x6000
	s_addc_u32 s3, s3, 0
	global_load_dword v112, v14, s[2:3]
	s_add_u32 s2, s2, 0x6000
	s_addc_u32 s3, s3, 0
	global_load_dword v113, v14, s[2:3]
	s_add_u32 s2, s2, 0x6000
	s_addc_u32 s3, s3, 0
	global_load_dword v114, v14, s[2:3]
	s_add_u32 s2, s2, 0x6000
	s_addc_u32 s3, s3, 0
	global_load_dword v115, v14, s[2:3]
	s_add_u32 s2, s2, 0x6000
	s_addc_u32 s3, s3, 0
	global_load_dword v116, v14, s[2:3]
	s_add_u32 s2, s2, 0x6000
	s_addc_u32 s3, s3, 0
	global_load_dword v117, v14, s[2:3]
	s_add_u32 s2, s2, 0x6000
	s_addc_u32 s3, s3, 0
	global_load_dword v118, v14, s[2:3]
	s_add_u32 s2, s2, 0x6000
	s_addc_u32 s3, s3, 0
	global_load_dword v119, v14, s[2:3]
	s_add_u32 s2, s2, 0x6000
	s_addc_u32 s3, s3, 0
	global_load_dword v120, v14, s[2:3]
	s_add_u32 s2, s2, 0x6000
	s_addc_u32 s3, s3, 0
	global_load_dword v121, v14, s[2:3]
	s_add_u32 s2, s2, 0x6000
	s_addc_u32 s3, s3, 0
	global_load_dword v122, v14, s[2:3]
	s_add_u32 s2, s2, 0x6000
	s_addc_u32 s3, s3, 0
	global_load_dword v123, v14, s[2:3]
	s_add_u32 s2, s2, 0x6000
	s_addc_u32 s3, s3, 0
	global_load_dword v124, v14, s[2:3]
	s_add_u32 s2, s2, 0x6000
	s_addc_u32 s3, s3, 0
	global_load_dword v125, v14, s[2:3]
	s_add_u32 s2, s2, 0x6000
	s_addc_u32 s3, s3, 0
	global_load_dword v126, v14, s[2:3]
	s_add_u32 s2, s2, 0x6000
	s_addc_u32 s3, s3, 0
	global_load_dword v127, v14, s[2:3]
	s_add_u32 s2, s2, 0x6000
	s_addc_u32 s3, s3, 0
	global_load_dword v128, v14, s[2:3]
	s_add_u32 s2, s2, 0x6000
	s_addc_u32 s3, s3, 0
	global_load_dword v129, v14, s[2:3]
	s_add_u32 s2, s2, 0x6000
	s_addc_u32 s3, s3, 0
	global_load_dword v130, v14, s[2:3]
	s_add_u32 s2, s2, 0x6000
	s_addc_u32 s3, s3, 0
	global_load_dword v131, v14, s[2:3]
	s_add_u32 s2, s2, 0x6000
	s_addc_u32 s3, s3, 0
	global_load_dword v132, v14, s[2:3]
	s_add_u32 s2, s2, 0x6000
	s_addc_u32 s3, s3, 0
	global_load_dword v133, v14, s[2:3]
	s_add_u32 s2, s2, 0x6000
	s_addc_u32 s3, s3, 0
	global_load_dword v134, v14, s[2:3]
	s_add_u32 s2, s2, 0x6000
	s_addc_u32 s3, s3, 0
	global_load_dword v135, v14, s[2:3]
	s_add_u32 s2, s2, 0x6000
	s_addc_u32 s3, s3, 0
	global_load_dword v136, v14, s[2:3]
	s_add_u32 s2, s2, 0x6000
	s_addc_u32 s3, s3, 0
	global_load_dword v137, v14, s[2:3]
	s_add_u32 s2, s2, 0x6000
	s_addc_u32 s3, s3, 0
	global_load_dword v138, v14, s[2:3]
	s_add_u32 s2, s2, 0x6000
	s_addc_u32 s3, s3, 0
	global_load_dword v139, v14, s[2:3]
	s_add_u32 s2, s2, 0x6000
	s_addc_u32 s3, s3, 0
	global_load_dword v140, v14, s[2:3]
	s_add_u32 s2, s2, 0x6000
	s_addc_u32 s3, s3, 0
	global_load_dword v141, v14, s[2:3]
	s_add_u32 s2, s2, 0x6000
	s_addc_u32 s3, s3, 0
	global_load_dword v160, v14, s[2:3]
	s_add_u32 s2, s2, 0x6000
	s_addc_u32 s3, s3, 0
	global_load_dword v161, v14, s[2:3]
	s_add_u32 s2, s2, 0x6000
	s_addc_u32 s3, s3, 0
	global_load_dword v162, v14, s[2:3]
	s_add_u32 s2, s2, 0x6000
	s_addc_u32 s3, s3, 0
	global_load_dword v163, v14, s[2:3]
	s_add_u32 s2, s2, 0x6000
	s_addc_u32 s3, s3, 0
	global_load_dword v164, v14, s[2:3]
	s_add_u32 s2, s2, 0x6000
	s_addc_u32 s3, s3, 0
	global_load_dword v165, v14, s[2:3]
	s_add_u32 s2, s2, 0x6000
	s_addc_u32 s3, s3, 0
	global_load_dword v166, v14, s[2:3]
	s_add_u32 s2, s2, 0x6000
	s_addc_u32 s3, s3, 0
	global_load_dword v167, v14, s[2:3]
	s_add_u32 s2, s2, 0x6000
	s_addc_u32 s3, s3, 0
	global_load_dword v168, v14, s[2:3]
	s_add_u32 s2, s2, 0x6000
	s_addc_u32 s3, s3, 0
	global_load_dword v169, v14, s[2:3]
	s_add_u32 s2, s2, 0x6000
	s_addc_u32 s3, s3, 0
	global_load_dword v170, v14, s[2:3]
	s_add_u32 s2, s2, 0x6000
	s_addc_u32 s3, s3, 0
	global_load_dword v171, v14, s[2:3]
	s_add_u32 s2, s2, 0x6000
	s_addc_u32 s3, s3, 0
	global_load_dword v172, v14, s[2:3]
	s_add_u32 s2, s2, 0x6000
	s_addc_u32 s3, s3, 0
	global_load_dword v173, v14, s[2:3]
	s_add_u32 s2, s2, 0x6000
	s_addc_u32 s3, s3, 0
	global_load_dword v174, v14, s[2:3]
	s_add_u32 s2, s2, 0x6000
	s_addc_u32 s3, s3, 0
	global_load_dword v175, v14, s[2:3]
	s_add_u32 s2, s2, 0x6000
	s_addc_u32 s3, s3, 0
	global_load_dword v176, v14, s[2:3]
	s_add_u32 s2, s2, 0x6000
	s_addc_u32 s3, s3, 0
	global_load_dword v177, v14, s[2:3]
	v_mov_b32_e32 v8, 0
	s_cmp_lg_u32 s11, 0
	s_cbranch_scc1 .Lp0_nobias
	s_mul_i32 s6, s0, 0x1800
	v_add_u32_e32 v16, s6, v2
	v_lshlrev_b32_e32 v16, 2, v16
	v_readlane_b32 s40, v247, 21
	v_readlane_b32 s41, v247, 22
	s_nop 4
	global_load_dword v8, v16, s[40:41]
.Lp0_nobias:
	v_or_b32_e32 v16, s12, v1
	v_lshrrev_b32_e32 v17, 6, v0
	v_add_u32_e32 v18, -1, v17
	v_lshl_add_u32 v18, v18, 10, v16
	v_lshlrev_b32_e32 v18, 2, v18
	v_lshlrev_b32_e32 v19, 2, v16
	v_add_u32_e32 v22, 0x3000, v19
	v_readlane_b32 s36, v247, 17
	v_readlane_b32 s37, v247, 18
	v_readlane_b32 s50, v247, 15
	v_readlane_b32 s51, v247, 16
	v_cmp_gt_u32_e32 vcc, 64, v0
	s_nop 4
	s_and_saveexec_b64 s[6:7], vcc
	global_load_dword v20, v19, s[36:37]
	global_load_dword v21, v22, s[50:51]
	s_andn2_b64 exec, s[6:7], vcc
	global_load_dword v20, v18, s[50:51]
	s_mov_b64 exec, s[6:7]
	s_waitcnt lgkmcnt(0)
	s_barrier
	s_waitcnt vmcnt(0)
	v_mul_f32_e32 v23, 0xbfb8aa3b, v20
	v_exp_f32_e32 v23, v23
	s_nop 0
	v_add_f32_e32 v23, 1.0, v23
	v_rcp_f32_e32 v23, v23
	s_nop 0
	v_mul_f32_e32 v20, v20, v23
	v_mul_f32_e32 v23, 0xbfb8aa3b, v21
	v_exp_f32_e32 v23, v23
	s_nop 0
	v_add_f32_e32 v23, 1.0, v23
	v_rcp_f32_e32 v23, v23
	s_nop 0
	v_mul_f32_e32 v21, v21, v23
	ds_write_b32 v10, v20
	s_and_saveexec_b64 s[6:7], vcc
	ds_write_b32 v10, v21 offset:1024
	s_mov_b64 exec, s[6:7]
	v_mov_b32_e32 v6, 0
	v_mov_b32_e32 v7, v6
	v_mov_b32_e32 v4, v6
	v_mov_b32_e32 v5, v6
	v_mov_b32_e32 v3, v6
	s_waitcnt lgkmcnt(0)
	s_barrier
.LBB0_35:
	v_mov_b32_e32 v11, 0
	ds_read_b128 v[12:15], v11
	ds_read_b128 v[16:19], v11 offset:16
	ds_read_b128 v[20:23], v11 offset:256
	ds_read_b128 v[24:27], v11 offset:272
	ds_read_b128 v[28:31], v11 offset:512
	ds_read_b128 v[32:35], v11 offset:528
	ds_read_b128 v[36:39], v11 offset:768
	ds_read_b128 v[40:43], v11 offset:784
	ds_read_b128 v[44:47], v11 offset:1024
	ds_read_b128 v[48:51], v11 offset:1040
	s_waitcnt lgkmcnt(0)
	v_fmac_f32_e32 v6, v96, v12
	v_fmac_f32_e32 v7, v96, v20
	v_fmac_f32_e32 v4, v96, v28
	v_fmac_f32_e32 v5, v96, v36
	v_fmac_f32_e32 v3, v96, v44
	v_fmac_f32_e32 v6, v97, v13
	v_fmac_f32_e32 v7, v97, v21
	v_fmac_f32_e32 v4, v97, v29
	v_fmac_f32_e32 v5, v97, v37
	v_fmac_f32_e32 v3, v97, v45
	v_fmac_f32_e32 v6, v98, v14
	v_fmac_f32_e32 v7, v98, v22
	v_fmac_f32_e32 v4, v98, v30
	v_fmac_f32_e32 v5, v98, v38
	v_fmac_f32_e32 v3, v98, v46
	v_fmac_f32_e32 v6, v99, v15
	v_fmac_f32_e32 v7, v99, v23
	v_fmac_f32_e32 v4, v99, v31
	v_fmac_f32_e32 v5, v99, v39
	v_fmac_f32_e32 v3, v99, v47
	v_fmac_f32_e32 v6, v100, v16
	v_fmac_f32_e32 v7, v100, v24
	v_fmac_f32_e32 v4, v100, v32
	v_fmac_f32_e32 v5, v100, v40
	v_fmac_f32_e32 v3, v100, v48
	v_fmac_f32_e32 v6, v101, v17
	v_fmac_f32_e32 v7, v101, v25
	v_fmac_f32_e32 v4, v101, v33
	v_fmac_f32_e32 v5, v101, v41
	v_fmac_f32_e32 v3, v101, v49
	v_fmac_f32_e32 v6, v102, v18
	v_fmac_f32_e32 v7, v102, v26
	v_fmac_f32_e32 v4, v102, v34
	v_fmac_f32_e32 v5, v102, v42
	v_fmac_f32_e32 v3, v102, v50
	v_fmac_f32_e32 v6, v103, v19
	v_fmac_f32_e32 v7, v103, v27
	v_fmac_f32_e32 v4, v103, v35
	v_fmac_f32_e32 v5, v103, v43
	v_fmac_f32_e32 v3, v103, v51
	ds_read_b128 v[12:15], v11 offset:32
	ds_read_b128 v[16:19], v11 offset:48
	ds_read_b128 v[20:23], v11 offset:288
	ds_read_b128 v[24:27], v11 offset:304
	ds_read_b128 v[28:31], v11 offset:544
	ds_read_b128 v[32:35], v11 offset:560
	ds_read_b128 v[36:39], v11 offset:800
	ds_read_b128 v[40:43], v11 offset:816
	ds_read_b128 v[44:47], v11 offset:1056
	ds_read_b128 v[48:51], v11 offset:1072
	s_waitcnt lgkmcnt(0)
	v_fmac_f32_e32 v6, v104, v12
	v_fmac_f32_e32 v7, v104, v20
	v_fmac_f32_e32 v4, v104, v28
	v_fmac_f32_e32 v5, v104, v36
	v_fmac_f32_e32 v3, v104, v44
	v_fmac_f32_e32 v6, v105, v13
	v_fmac_f32_e32 v7, v105, v21
	v_fmac_f32_e32 v4, v105, v29
	v_fmac_f32_e32 v5, v105, v37
	v_fmac_f32_e32 v3, v105, v45
	v_fmac_f32_e32 v6, v106, v14
	v_fmac_f32_e32 v7, v106, v22
	v_fmac_f32_e32 v4, v106, v30
	v_fmac_f32_e32 v5, v106, v38
	v_fmac_f32_e32 v3, v106, v46
	v_fmac_f32_e32 v6, v107, v15
	v_fmac_f32_e32 v7, v107, v23
	v_fmac_f32_e32 v4, v107, v31
	v_fmac_f32_e32 v5, v107, v39
	v_fmac_f32_e32 v3, v107, v47
	v_fmac_f32_e32 v6, v108, v16
	v_fmac_f32_e32 v7, v108, v24
	v_fmac_f32_e32 v4, v108, v32
	v_fmac_f32_e32 v5, v108, v40
	v_fmac_f32_e32 v3, v108, v48
	v_fmac_f32_e32 v6, v109, v17
	v_fmac_f32_e32 v7, v109, v25
	v_fmac_f32_e32 v4, v109, v33
	v_fmac_f32_e32 v5, v109, v41
	v_fmac_f32_e32 v3, v109, v49
	v_fmac_f32_e32 v6, v110, v18
	v_fmac_f32_e32 v7, v110, v26
	v_fmac_f32_e32 v4, v110, v34
	v_fmac_f32_e32 v5, v110, v42
	v_fmac_f32_e32 v3, v110, v50
	v_fmac_f32_e32 v6, v111, v19
	v_fmac_f32_e32 v7, v111, v27
	v_fmac_f32_e32 v4, v111, v35
	v_fmac_f32_e32 v5, v111, v43
	v_fmac_f32_e32 v3, v111, v51
	ds_read_b128 v[12:15], v11 offset:64
	ds_read_b128 v[16:19], v11 offset:80
	ds_read_b128 v[20:23], v11 offset:320
	ds_read_b128 v[24:27], v11 offset:336
	ds_read_b128 v[28:31], v11 offset:576
	ds_read_b128 v[32:35], v11 offset:592
	ds_read_b128 v[36:39], v11 offset:832
	ds_read_b128 v[40:43], v11 offset:848
	ds_read_b128 v[44:47], v11 offset:1088
	ds_read_b128 v[48:51], v11 offset:1104
	s_waitcnt lgkmcnt(0)
	v_fmac_f32_e32 v6, v112, v12
	v_fmac_f32_e32 v7, v112, v20
	v_fmac_f32_e32 v4, v112, v28
	v_fmac_f32_e32 v5, v112, v36
	v_fmac_f32_e32 v3, v112, v44
	v_fmac_f32_e32 v6, v113, v13
	v_fmac_f32_e32 v7, v113, v21
	v_fmac_f32_e32 v4, v113, v29
	v_fmac_f32_e32 v5, v113, v37
	v_fmac_f32_e32 v3, v113, v45
	v_fmac_f32_e32 v6, v114, v14
	v_fmac_f32_e32 v7, v114, v22
	v_fmac_f32_e32 v4, v114, v30
	v_fmac_f32_e32 v5, v114, v38
	v_fmac_f32_e32 v3, v114, v46
	v_fmac_f32_e32 v6, v115, v15
	v_fmac_f32_e32 v7, v115, v23
	v_fmac_f32_e32 v4, v115, v31
	v_fmac_f32_e32 v5, v115, v39
	v_fmac_f32_e32 v3, v115, v47
	v_fmac_f32_e32 v6, v116, v16
	v_fmac_f32_e32 v7, v116, v24
	v_fmac_f32_e32 v4, v116, v32
	v_fmac_f32_e32 v5, v116, v40
	v_fmac_f32_e32 v3, v116, v48
	v_fmac_f32_e32 v6, v117, v17
	v_fmac_f32_e32 v7, v117, v25
	v_fmac_f32_e32 v4, v117, v33
	v_fmac_f32_e32 v5, v117, v41
	v_fmac_f32_e32 v3, v117, v49
	v_fmac_f32_e32 v6, v118, v18
	v_fmac_f32_e32 v7, v118, v26
	v_fmac_f32_e32 v4, v118, v34
	v_fmac_f32_e32 v5, v118, v42
	v_fmac_f32_e32 v3, v118, v50
	v_fmac_f32_e32 v6, v119, v19
	v_fmac_f32_e32 v7, v119, v27
	v_fmac_f32_e32 v4, v119, v35
	v_fmac_f32_e32 v5, v119, v43
	v_fmac_f32_e32 v3, v119, v51
	ds_read_b128 v[12:15], v11 offset:96
	ds_read_b128 v[16:19], v11 offset:112
	ds_read_b128 v[20:23], v11 offset:352
	ds_read_b128 v[24:27], v11 offset:368
	ds_read_b128 v[28:31], v11 offset:608
	ds_read_b128 v[32:35], v11 offset:624
	ds_read_b128 v[36:39], v11 offset:864
	ds_read_b128 v[40:43], v11 offset:880
	ds_read_b128 v[44:47], v11 offset:1120
	ds_read_b128 v[48:51], v11 offset:1136
	s_waitcnt lgkmcnt(0)
	v_fmac_f32_e32 v6, v120, v12
	v_fmac_f32_e32 v7, v120, v20
	v_fmac_f32_e32 v4, v120, v28
	v_fmac_f32_e32 v5, v120, v36
	v_fmac_f32_e32 v3, v120, v44
	v_fmac_f32_e32 v6, v121, v13
	v_fmac_f32_e32 v7, v121, v21
	v_fmac_f32_e32 v4, v121, v29
	v_fmac_f32_e32 v5, v121, v37
	v_fmac_f32_e32 v3, v121, v45
	v_fmac_f32_e32 v6, v122, v14
	v_fmac_f32_e32 v7, v122, v22
	v_fmac_f32_e32 v4, v122, v30
	v_fmac_f32_e32 v5, v122, v38
	v_fmac_f32_e32 v3, v122, v46
	v_fmac_f32_e32 v6, v123, v15
	v_fmac_f32_e32 v7, v123, v23
	v_fmac_f32_e32 v4, v123, v31
	v_fmac_f32_e32 v5, v123, v39
	v_fmac_f32_e32 v3, v123, v47
	v_fmac_f32_e32 v6, v124, v16
	v_fmac_f32_e32 v7, v124, v24
	v_fmac_f32_e32 v4, v124, v32
	v_fmac_f32_e32 v5, v124, v40
	v_fmac_f32_e32 v3, v124, v48
	v_fmac_f32_e32 v6, v125, v17
	v_fmac_f32_e32 v7, v125, v25
	v_fmac_f32_e32 v4, v125, v33
	v_fmac_f32_e32 v5, v125, v41
	v_fmac_f32_e32 v3, v125, v49
	v_fmac_f32_e32 v6, v126, v18
	v_fmac_f32_e32 v7, v126, v26
	v_fmac_f32_e32 v4, v126, v34
	v_fmac_f32_e32 v5, v126, v42
	v_fmac_f32_e32 v3, v126, v50
	v_fmac_f32_e32 v6, v127, v19
	v_fmac_f32_e32 v7, v127, v27
	v_fmac_f32_e32 v4, v127, v35
	v_fmac_f32_e32 v5, v127, v43
	v_fmac_f32_e32 v3, v127, v51
	ds_read_b128 v[12:15], v11 offset:128
	ds_read_b128 v[16:19], v11 offset:144
	ds_read_b128 v[20:23], v11 offset:384
	ds_read_b128 v[24:27], v11 offset:400
	ds_read_b128 v[28:31], v11 offset:640
	ds_read_b128 v[32:35], v11 offset:656
	ds_read_b128 v[36:39], v11 offset:896
	ds_read_b128 v[40:43], v11 offset:912
	ds_read_b128 v[44:47], v11 offset:1152
	ds_read_b128 v[48:51], v11 offset:1168
	s_waitcnt lgkmcnt(0)
	v_fmac_f32_e32 v6, v128, v12
	v_fmac_f32_e32 v7, v128, v20
	v_fmac_f32_e32 v4, v128, v28
	v_fmac_f32_e32 v5, v128, v36
	v_fmac_f32_e32 v3, v128, v44
	v_fmac_f32_e32 v6, v129, v13
	v_fmac_f32_e32 v7, v129, v21
	v_fmac_f32_e32 v4, v129, v29
	v_fmac_f32_e32 v5, v129, v37
	v_fmac_f32_e32 v3, v129, v45
	v_fmac_f32_e32 v6, v130, v14
	v_fmac_f32_e32 v7, v130, v22
	v_fmac_f32_e32 v4, v130, v30
	v_fmac_f32_e32 v5, v130, v38
	v_fmac_f32_e32 v3, v130, v46
	v_fmac_f32_e32 v6, v131, v15
	v_fmac_f32_e32 v7, v131, v23
	v_fmac_f32_e32 v4, v131, v31
	v_fmac_f32_e32 v5, v131, v39
	v_fmac_f32_e32 v3, v131, v47
	v_fmac_f32_e32 v6, v132, v16
	v_fmac_f32_e32 v7, v132, v24
	v_fmac_f32_e32 v4, v132, v32
	v_fmac_f32_e32 v5, v132, v40
	v_fmac_f32_e32 v3, v132, v48
	v_fmac_f32_e32 v6, v133, v17
	v_fmac_f32_e32 v7, v133, v25
	v_fmac_f32_e32 v4, v133, v33
	v_fmac_f32_e32 v5, v133, v41
	v_fmac_f32_e32 v3, v133, v49
	v_fmac_f32_e32 v6, v134, v18
	v_fmac_f32_e32 v7, v134, v26
	v_fmac_f32_e32 v4, v134, v34
	v_fmac_f32_e32 v5, v134, v42
	v_fmac_f32_e32 v3, v134, v50
	v_fmac_f32_e32 v6, v135, v19
	v_fmac_f32_e32 v7, v135, v27
	v_fmac_f32_e32 v4, v135, v35
	v_fmac_f32_e32 v5, v135, v43
	v_fmac_f32_e32 v3, v135, v51
	ds_read_b128 v[12:15], v11 offset:160
	ds_read_b128 v[16:19], v11 offset:176
	ds_read_b128 v[20:23], v11 offset:416
	ds_read_b128 v[24:27], v11 offset:432
	ds_read_b128 v[28:31], v11 offset:672
	ds_read_b128 v[32:35], v11 offset:688
	ds_read_b128 v[36:39], v11 offset:928
	ds_read_b128 v[40:43], v11 offset:944
	ds_read_b128 v[44:47], v11 offset:1184
	ds_read_b128 v[48:51], v11 offset:1200
	s_waitcnt lgkmcnt(0)
	v_fmac_f32_e32 v6, v136, v12
	v_fmac_f32_e32 v7, v136, v20
	v_fmac_f32_e32 v4, v136, v28
	v_fmac_f32_e32 v5, v136, v36
	v_fmac_f32_e32 v3, v136, v44
	v_fmac_f32_e32 v6, v137, v13
	v_fmac_f32_e32 v7, v137, v21
	v_fmac_f32_e32 v4, v137, v29
	v_fmac_f32_e32 v5, v137, v37
	v_fmac_f32_e32 v3, v137, v45
	v_fmac_f32_e32 v6, v138, v14
	v_fmac_f32_e32 v7, v138, v22
	v_fmac_f32_e32 v4, v138, v30
	v_fmac_f32_e32 v5, v138, v38
	v_fmac_f32_e32 v3, v138, v46
	v_fmac_f32_e32 v6, v139, v15
	v_fmac_f32_e32 v7, v139, v23
	v_fmac_f32_e32 v4, v139, v31
	v_fmac_f32_e32 v5, v139, v39
	v_fmac_f32_e32 v3, v139, v47
	v_fmac_f32_e32 v6, v140, v16
	v_fmac_f32_e32 v7, v140, v24
	v_fmac_f32_e32 v4, v140, v32
	v_fmac_f32_e32 v5, v140, v40
	v_fmac_f32_e32 v3, v140, v48
	v_fmac_f32_e32 v6, v141, v17
	v_fmac_f32_e32 v7, v141, v25
	v_fmac_f32_e32 v4, v141, v33
	v_fmac_f32_e32 v5, v141, v41
	v_fmac_f32_e32 v3, v141, v49
	v_fmac_f32_e32 v6, v160, v18
	v_fmac_f32_e32 v7, v160, v26
	v_fmac_f32_e32 v4, v160, v34
	v_fmac_f32_e32 v5, v160, v42
	v_fmac_f32_e32 v3, v160, v50
	v_fmac_f32_e32 v6, v161, v19
	v_fmac_f32_e32 v7, v161, v27
	v_fmac_f32_e32 v4, v161, v35
	v_fmac_f32_e32 v5, v161, v43
	v_fmac_f32_e32 v3, v161, v51
	ds_read_b128 v[12:15], v11 offset:192
	ds_read_b128 v[16:19], v11 offset:208
	ds_read_b128 v[20:23], v11 offset:448
	ds_read_b128 v[24:27], v11 offset:464
	ds_read_b128 v[28:31], v11 offset:704
	ds_read_b128 v[32:35], v11 offset:720
	ds_read_b128 v[36:39], v11 offset:960
	ds_read_b128 v[40:43], v11 offset:976
	ds_read_b128 v[44:47], v11 offset:1216
	ds_read_b128 v[48:51], v11 offset:1232
	s_waitcnt lgkmcnt(0)
	v_fmac_f32_e32 v6, v162, v12
	v_fmac_f32_e32 v7, v162, v20
	v_fmac_f32_e32 v4, v162, v28
	v_fmac_f32_e32 v5, v162, v36
	v_fmac_f32_e32 v3, v162, v44
	v_fmac_f32_e32 v6, v163, v13
	v_fmac_f32_e32 v7, v163, v21
	v_fmac_f32_e32 v4, v163, v29
	v_fmac_f32_e32 v5, v163, v37
	v_fmac_f32_e32 v3, v163, v45
	v_fmac_f32_e32 v6, v164, v14
	v_fmac_f32_e32 v7, v164, v22
	v_fmac_f32_e32 v4, v164, v30
	v_fmac_f32_e32 v5, v164, v38
	v_fmac_f32_e32 v3, v164, v46
	v_fmac_f32_e32 v6, v165, v15
	v_fmac_f32_e32 v7, v165, v23
	v_fmac_f32_e32 v4, v165, v31
	v_fmac_f32_e32 v5, v165, v39
	v_fmac_f32_e32 v3, v165, v47
	v_fmac_f32_e32 v6, v166, v16
	v_fmac_f32_e32 v7, v166, v24
	v_fmac_f32_e32 v4, v166, v32
	v_fmac_f32_e32 v5, v166, v40
	v_fmac_f32_e32 v3, v166, v48
	v_fmac_f32_e32 v6, v167, v17
	v_fmac_f32_e32 v7, v167, v25
	v_fmac_f32_e32 v4, v167, v33
	v_fmac_f32_e32 v5, v167, v41
	v_fmac_f32_e32 v3, v167, v49
	v_fmac_f32_e32 v6, v168, v18
	v_fmac_f32_e32 v7, v168, v26
	v_fmac_f32_e32 v4, v168, v34
	v_fmac_f32_e32 v5, v168, v42
	v_fmac_f32_e32 v3, v168, v50
	v_fmac_f32_e32 v6, v169, v19
	v_fmac_f32_e32 v7, v169, v27
	v_fmac_f32_e32 v4, v169, v35
	v_fmac_f32_e32 v5, v169, v43
	v_fmac_f32_e32 v3, v169, v51
	ds_read_b128 v[12:15], v11 offset:224
	ds_read_b128 v[16:19], v11 offset:240
	ds_read_b128 v[20:23], v11 offset:480
	ds_read_b128 v[24:27], v11 offset:496
	ds_read_b128 v[28:31], v11 offset:736
	ds_read_b128 v[32:35], v11 offset:752
	ds_read_b128 v[36:39], v11 offset:992
	ds_read_b128 v[40:43], v11 offset:1008
	ds_read_b128 v[44:47], v11 offset:1248
	ds_read_b128 v[48:51], v11 offset:1264
	s_waitcnt lgkmcnt(0)
	v_fmac_f32_e32 v6, v170, v12
	v_fmac_f32_e32 v7, v170, v20
	v_fmac_f32_e32 v4, v170, v28
	v_fmac_f32_e32 v5, v170, v36
	v_fmac_f32_e32 v3, v170, v44
	v_fmac_f32_e32 v6, v171, v13
	v_fmac_f32_e32 v7, v171, v21
	v_fmac_f32_e32 v4, v171, v29
	v_fmac_f32_e32 v5, v171, v37
	v_fmac_f32_e32 v3, v171, v45
	v_fmac_f32_e32 v6, v172, v14
	v_fmac_f32_e32 v7, v172, v22
	v_fmac_f32_e32 v4, v172, v30
	v_fmac_f32_e32 v5, v172, v38
	v_fmac_f32_e32 v3, v172, v46
	v_fmac_f32_e32 v6, v173, v15
	v_fmac_f32_e32 v7, v173, v23
	v_fmac_f32_e32 v4, v173, v31
	v_fmac_f32_e32 v5, v173, v39
	v_fmac_f32_e32 v3, v173, v47
	v_fmac_f32_e32 v6, v174, v16
	v_fmac_f32_e32 v7, v174, v24
	v_fmac_f32_e32 v4, v174, v32
	v_fmac_f32_e32 v5, v174, v40
	v_fmac_f32_e32 v3, v174, v48
	v_fmac_f32_e32 v6, v175, v17
	v_fmac_f32_e32 v7, v175, v25
	v_fmac_f32_e32 v4, v175, v33
	v_fmac_f32_e32 v5, v175, v41
	v_fmac_f32_e32 v3, v175, v49
	v_fmac_f32_e32 v6, v176, v18
	v_fmac_f32_e32 v7, v176, v26
	v_fmac_f32_e32 v4, v176, v34
	v_fmac_f32_e32 v5, v176, v42
	v_fmac_f32_e32 v3, v176, v50
	v_fmac_f32_e32 v6, v177, v19
	v_fmac_f32_e32 v7, v177, v27
	v_fmac_f32_e32 v4, v177, v35
	v_fmac_f32_e32 v5, v177, v43
	v_fmac_f32_e32 v3, v177, v51
	s_branch .LBB0_28
